# in-proj n_gate tile (24 useful of 256 columns): K-loop variant that issues only the MFMAs / fragment reads its epilogue consumes
# speedup vs baseline: 1.0983x; 1.0010x over previous
; #define G_LDA(dst, ih, ks) _Pragma("unroll") for (int i = 0; i < 4; ++i) dst[i] = mk8(*(const u32x4*)(stage + ra + (((ih) * 4 + i) * 2 + (ks)) * 1024))
; #define G_LDB(dst, ks) _Pragma("unroll") for (int j = 0; j < 4; ++j) dst[j] = mk8(*(const u32x4*)(stage + TILE_B + rb + (j * 2 + (ks)) * 1024))
; #define G_MMA(ih, A, B) do { _Pragma("unroll") for (int i = 0; i < 4; ++i) _Pragma("unroll") for (int j = 0; j < 4; ++j) acc[(ih) * 4 + i][j] = MFMA16(A[i], B[j], acc[(ih) * 4 + i][j]); } while (0)
; DI void g_compute(const unsigned char* stage, int ra, int rb, f32x4 (&acc)[8][4]) {
;   bf16x8 b0[4], b1[4], a0[4], a1[4];
;   G_LDB(b0, 0); G_LDA(a0, 0, 0);
;   __builtin_amdgcn_sched_barrier(0);
;   G_LDA(a1, 1, 0);
;   G_MMA(0, a0, b0);
;   __builtin_amdgcn_sched_barrier(0);
;   G_LDB(b1, 1); G_LDA(a0, 0, 1);
;   G_MMA(1, a1, b0);
;   __builtin_amdgcn_sched_barrier(0);
;   G_LDA(a1, 1, 1);
;   G_MMA(0, a0, b1);
;   __builtin_amdgcn_sched_barrier(0);
;   G_MMA(1, a1, b1);
;   __builtin_amdgcn_sched_barrier(0);
; }
;     ...
;   for (int kt = 0; kt < KT; kt += 2) {
;     g_dma(base, off, (kt + 1) * kstep, buf1, w);
;     g_compute(buf0, ra, rb, acc);
;     asm volatile("s_waitcnt vmcnt(0)" ::: "memory");
;     __syncthreads();
;     const bool last = kt + 2 >= KT;
;     g_dma(last ? nbase : base, off, last ? 0 : (kt + 2) * kstep, buf0, w);
;     g_compute(buf1, ra, rb, acc);
;     asm volatile("s_waitcnt vmcnt(0)" ::: "memory");
;     __syncthreads();
.LgA_k1done:
	s_add_u32 s40, s40, 0x80
	s_addc_u32 s41, s41, 0
	ds_read_b128 v[146:149], v198
	ds_read_b128 v[150:153], v198 offset:2048
	ds_read_b128 v[154:157], v198 offset:4096
	ds_read_b128 v[158:161], v198 offset:6144
	ds_read_b128 v[164:167], v196
	ds_read_b128 v[168:171], v196 offset:2048
	ds_read_b128 v[172:175], v196 offset:4096
	ds_read_b128 v[176:179], v196 offset:6144
	v_readfirstlane_b32 s48, v202
	s_nop 0
	s_cmp_eq_u32 s48, 20
	s_cbranch_scc0 .LgA_full
	v_readfirstlane_b32 s48, v210
	s_nop 0
	s_cmp_lt_u32 s48, 0x100
	s_cbranch_scc0 .LgA_lite1
	s_mov_b32 s46, 0
.LgAl0_loop:
	s_waitcnt lgkmcnt(0)
	v_mfma_f32_16x16x32_bf16 v[126:129], v[164:167], v[146:149], v[126:129]
	v_mfma_f32_16x16x32_bf16 v[118:121], v[164:167], v[150:153], v[118:121]
	v_mfma_f32_16x16x32_bf16 v[110:113], v[164:167], v[154:157], v[110:113]
	v_mfma_f32_16x16x32_bf16 v[102:105], v[164:167], v[158:161], v[102:105]
	v_mfma_f32_16x16x32_bf16 v[122:125], v[168:171], v[146:149], v[122:125]
	v_mfma_f32_16x16x32_bf16 v[114:117], v[168:171], v[150:153], v[114:117]
	v_mfma_f32_16x16x32_bf16 v[106:109], v[168:171], v[154:157], v[106:109]
	v_mfma_f32_16x16x32_bf16 v[98:101], v[168:171], v[158:161], v[98:101]
	s_waitcnt lgkmcnt(0)
	ds_read_b128 v[216:219], v198 offset:1024
	ds_read_b128 v[220:223], v198 offset:3072
	ds_read_b128 v[224:227], v198 offset:5120
	ds_read_b128 v[240:243], v198 offset:7168
	ds_read_b128 v[164:167], v196 offset:1024
	ds_read_b128 v[168:171], v196 offset:3072
	s_waitcnt lgkmcnt(0)
	v_mfma_f32_16x16x32_bf16 v[126:129], v[164:167], v[216:219], v[126:129]
	v_mfma_f32_16x16x32_bf16 v[118:121], v[164:167], v[220:223], v[118:121]
	v_mfma_f32_16x16x32_bf16 v[110:113], v[164:167], v[224:227], v[110:113]
	v_mfma_f32_16x16x32_bf16 v[102:105], v[164:167], v[240:243], v[102:105]
	v_mfma_f32_16x16x32_bf16 v[122:125], v[168:171], v[216:219], v[122:125]
	v_mfma_f32_16x16x32_bf16 v[114:117], v[168:171], v[220:223], v[114:117]
	v_mfma_f32_16x16x32_bf16 v[106:109], v[168:171], v[224:227], v[106:109]
	v_mfma_f32_16x16x32_bf16 v[98:101], v[168:171], v[240:243], v[98:101]
	s_waitcnt lgkmcnt(0)
	s_cmp_eq_u32 s47, 0
	s_cbranch_scc1 .LgAl0_w0
	s_mov_b32 s47, 0
	s_waitcnt vmcnt(16)
	s_branch .LgAl0_w1

; #define G_LDA(dst, ih, ks) _Pragma("unroll") for (int i = 0; i < 4; ++i) dst[i] = mk8(*(const u32x4*)(stage + ra + (((ih) * 4 + i) * 2 + (ks)) * 1024))
; #define G_LDB(dst, ks) _Pragma("unroll") for (int j = 0; j < 4; ++j) dst[j] = mk8(*(const u32x4*)(stage + TILE_B + rb + (j * 2 + (ks)) * 1024))
; #define G_MMA(ih, A, B) do { _Pragma("unroll") for (int i = 0; i < 4; ++i) _Pragma("unroll") for (int j = 0; j < 4; ++j) acc[(ih) * 4 + i][j] = MFMA16(A[i], B[j], acc[(ih) * 4 + i][j]); } while (0)
; DI void g_compute(const unsigned char* stage, int ra, int rb, f32x4 (&acc)[8][4]) {
;   bf16x8 b0[4], b1[4], a0[4], a1[4];
;   G_LDB(b0, 0); G_LDA(a0, 0, 0);
;   __builtin_amdgcn_sched_barrier(0);
;   G_LDA(a1, 1, 0);
;   G_MMA(0, a0, b0);
;   __builtin_amdgcn_sched_barrier(0);
;   G_LDB(b1, 1); G_LDA(a0, 0, 1);
;   G_MMA(1, a1, b0);
;   __builtin_amdgcn_sched_barrier(0);
;   G_LDA(a1, 1, 1);
;   G_MMA(0, a0, b1);
;   __builtin_amdgcn_sched_barrier(0);
;   G_MMA(1, a1, b1);
;   __builtin_amdgcn_sched_barrier(0);
; }
;     ...
;   for (int kt = 0; kt < KT; kt += 2) {
;     g_dma(base, off, (kt + 1) * kstep, buf1, w);
;     g_compute(buf0, ra, rb, acc);
;     asm volatile("s_waitcnt vmcnt(0)" ::: "memory");
;     __syncthreads();
;     const bool last = kt + 2 >= KT;
;     g_dma(last ? nbase : base, off, last ? 0 : (kt + 2) * kstep, buf0, w);
;     g_compute(buf1, ra, rb, acc);
;     asm volatile("s_waitcnt vmcnt(0)" ::: "memory");
;     __syncthreads();
.LgAl0_w1:
	s_barrier
	s_add_i32 m0, s44, 0x0
	global_load_lds_dwordx4 v244, s[40:41]
	ds_read_b128 v[146:149], v199
	ds_read_b128 v[150:153], v199 offset:2048
	s_add_i32 m0, s44, 0x400
	global_load_lds_dwordx4 v245, s[40:41]
	ds_read_b128 v[154:157], v199 offset:4096
	ds_read_b128 v[158:161], v199 offset:6144
	s_add_i32 m0, s44, 0x800
	global_load_lds_dwordx4 v246, s[40:41]
	ds_read_b128 v[164:167], v197
	ds_read_b128 v[168:171], v197 offset:2048
	s_add_i32 m0, s44, 0xc00
	global_load_lds_dwordx4 v247, s[40:41]
	s_add_i32 m0, s44, 0x1000
	global_load_lds_dwordx4 v248, s[40:41]
	s_add_i32 m0, s44, 0x1400
	global_load_lds_dwordx4 v249, s[40:41]
	s_add_i32 m0, s44, 0x1800
	global_load_lds_dwordx4 v250, s[40:41]
	s_add_i32 m0, s44, 0x1c00
	global_load_lds_dwordx4 v251, s[40:41]
	s_add_u32 s40, s40, 0x80
	s_addc_u32 s41, s41, 0
	s_waitcnt lgkmcnt(0)
	v_mfma_f32_16x16x32_bf16 v[126:129], v[164:167], v[146:149], v[126:129]
	v_mfma_f32_16x16x32_bf16 v[118:121], v[164:167], v[150:153], v[118:121]
	v_mfma_f32_16x16x32_bf16 v[110:113], v[164:167], v[154:157], v[110:113]
	v_mfma_f32_16x16x32_bf16 v[102:105], v[164:167], v[158:161], v[102:105]
	v_mfma_f32_16x16x32_bf16 v[122:125], v[168:171], v[146:149], v[122:125]
	v_mfma_f32_16x16x32_bf16 v[114:117], v[168:171], v[150:153], v[114:117]
	v_mfma_f32_16x16x32_bf16 v[106:109], v[168:171], v[154:157], v[106:109]
	v_mfma_f32_16x16x32_bf16 v[98:101], v[168:171], v[158:161], v[98:101]
	s_waitcnt lgkmcnt(0)
	ds_read_b128 v[216:219], v199 offset:1024
	ds_read_b128 v[220:223], v199 offset:3072
	ds_read_b128 v[224:227], v199 offset:5120
	ds_read_b128 v[240:243], v199 offset:7168
	ds_read_b128 v[164:167], v197 offset:1024
	ds_read_b128 v[168:171], v197 offset:3072
	s_waitcnt lgkmcnt(0)
	v_mfma_f32_16x16x32_bf16 v[126:129], v[164:167], v[216:219], v[126:129]
	v_mfma_f32_16x16x32_bf16 v[118:121], v[164:167], v[220:223], v[118:121]
	v_mfma_f32_16x16x32_bf16 v[110:113], v[164:167], v[224:227], v[110:113]
	v_mfma_f32_16x16x32_bf16 v[102:105], v[164:167], v[240:243], v[102:105]
	v_mfma_f32_16x16x32_bf16 v[122:125], v[168:171], v[216:219], v[122:125]
	v_mfma_f32_16x16x32_bf16 v[114:117], v[168:171], v[220:223], v[114:117]
	v_mfma_f32_16x16x32_bf16 v[106:109], v[168:171], v[224:227], v[106:109]
	v_mfma_f32_16x16x32_bf16 v[98:101], v[168:171], v[240:243], v[98:101]
	s_waitcnt lgkmcnt(0)
	s_waitcnt vmcnt(0)
	s_barrier
	s_add_i32 m0, s45, 0x0
	global_load_lds_dwordx4 v244, s[40:41]
	ds_read_b128 v[146:149], v198
	ds_read_b128 v[150:153], v198 offset:2048
	s_add_i32 m0, s45, 0x400
	global_load_lds_dwordx4 v245, s[40:41]
	ds_read_b128 v[154:157], v198 offset:4096
	ds_read_b128 v[158:161], v198 offset:6144
	s_add_i32 m0, s45, 0x800
	global_load_lds_dwordx4 v246, s[40:41]
	ds_read_b128 v[164:167], v196
	ds_read_b128 v[168:171], v196 offset:2048
	s_add_i32 m0, s45, 0xc00
	global_load_lds_dwordx4 v247, s[40:41]
	s_add_i32 m0, s45, 0x1000
	global_load_lds_dwordx4 v248, s[40:41]
	s_add_i32 m0, s45, 0x1400
	global_load_lds_dwordx4 v249, s[40:41]
	s_add_i32 m0, s45, 0x1800
	global_load_lds_dwordx4 v250, s[40:41]
	s_add_i32 m0, s45, 0x1c00
	global_load_lds_dwordx4 v251, s[40:41]
	s_add_u32 s40, s40, 0x80
	s_addc_u32 s41, s41, 0
	s_add_i32 s46, s46, 1
	s_cmp_lt_u32 s46, 7
	s_cbranch_scc1 .LgAl0_loop
	s_waitcnt lgkmcnt(0)
	v_mfma_f32_16x16x32_bf16 v[126:129], v[164:167], v[146:149], v[126:129]
	v_mfma_f32_16x16x32_bf16 v[118:121], v[164:167], v[150:153], v[118:121]
	v_mfma_f32_16x16x32_bf16 v[110:113], v[164:167], v[154:157], v[110:113]
	v_mfma_f32_16x16x32_bf16 v[102:105], v[164:167], v[158:161], v[102:105]
	v_mfma_f32_16x16x32_bf16 v[122:125], v[168:171], v[146:149], v[122:125]
	v_mfma_f32_16x16x32_bf16 v[114:117], v[168:171], v[150:153], v[114:117]
	v_mfma_f32_16x16x32_bf16 v[106:109], v[168:171], v[154:157], v[106:109]
	v_mfma_f32_16x16x32_bf16 v[98:101], v[168:171], v[158:161], v[98:101]
	s_waitcnt lgkmcnt(0)
	ds_read_b128 v[216:219], v198 offset:1024
	ds_read_b128 v[220:223], v198 offset:3072
	ds_read_b128 v[224:227], v198 offset:5120
	ds_read_b128 v[240:243], v198 offset:7168
	ds_read_b128 v[164:167], v196 offset:1024
	ds_read_b128 v[168:171], v196 offset:3072
	s_waitcnt lgkmcnt(0)
	v_mfma_f32_16x16x32_bf16 v[126:129], v[164:167], v[216:219], v[126:129]
	v_mfma_f32_16x16x32_bf16 v[118:121], v[164:167], v[220:223], v[118:121]
	v_mfma_f32_16x16x32_bf16 v[110:113], v[164:167], v[224:227], v[110:113]
	v_mfma_f32_16x16x32_bf16 v[102:105], v[164:167], v[240:243], v[102:105]
	v_mfma_f32_16x16x32_bf16 v[122:125], v[168:171], v[216:219], v[122:125]
	v_mfma_f32_16x16x32_bf16 v[114:117], v[168:171], v[220:223], v[114:117]
	v_mfma_f32_16x16x32_bf16 v[106:109], v[168:171], v[224:227], v[106:109]
	v_mfma_f32_16x16x32_bf16 v[98:101], v[168:171], v[240:243], v[98:101]
	s_waitcnt lgkmcnt(0)
	s_waitcnt vmcnt(0)
	s_barrier
; #define G_LDA(dst, ih, ks) _Pragma("unroll") for (int i = 0; i < 4; ++i) dst[i] = mk8(*(const u32x4*)(stage + ra + (((ih) * 4 + i) * 2 + (ks)) * 1024))
; #define G_LDB(dst, ks) _Pragma("unroll") for (int j = 0; j < 4; ++j) dst[j] = mk8(*(const u32x4*)(stage + TILE_B + rb + (j * 2 + (ks)) * 1024))
; #define G_MMA(ih, A, B) do { _Pragma("unroll") for (int i = 0; i < 4; ++i) _Pragma("unroll") for (int j = 0; j < 4; ++j) acc[(ih) * 4 + i][j] = MFMA16(A[i], B[j], acc[(ih) * 4 + i][j]); } while (0)
; DI void g_compute(const unsigned char* stage, int ra, int rb, f32x4 (&acc)[8][4]) {
;   bf16x8 b0[4], b1[4], a0[4], a1[4];
;   G_LDB(b0, 0); G_LDA(a0, 0, 0);
;   __builtin_amdgcn_sched_barrier(0);
;   G_LDA(a1, 1, 0);
;   G_MMA(0, a0, b0);
;   __builtin_amdgcn_sched_barrier(0);
;   G_LDB(b1, 1); G_LDA(a0, 0, 1);
;   G_MMA(1, a1, b0);
;   __builtin_amdgcn_sched_barrier(0);
;   G_LDA(a1, 1, 1);
;   G_MMA(0, a0, b1);
;   __builtin_amdgcn_sched_barrier(0);
;   G_MMA(1, a1, b1);
;   __builtin_amdgcn_sched_barrier(0);
; }
;     ...
;   for (int kt = 0; kt < KT; kt += 2) {
;     g_dma(base, off, (kt + 1) * kstep, buf1, w);
;     g_compute(buf0, ra, rb, acc);
;     asm volatile("s_waitcnt vmcnt(0)" ::: "memory");
;     __syncthreads();
;     const bool last = kt + 2 >= KT;
;     g_dma(last ? nbase : base, off, last ? 0 : (kt + 2) * kstep, buf0, w);
;     g_compute(buf1, ra, rb, acc);
;     asm volatile("s_waitcnt vmcnt(0)" ::: "memory");
;     __syncthreads();
;   }
	s_add_i32 m0, s44, 0x0
	global_load_lds_dwordx4 v244, s[42:43]
	ds_read_b128 v[146:149], v199
	ds_read_b128 v[150:153], v199 offset:2048
	s_add_i32 m0, s44, 0x400
	global_load_lds_dwordx4 v245, s[42:43]
	ds_read_b128 v[154:157], v199 offset:4096
	ds_read_b128 v[158:161], v199 offset:6144
	s_add_i32 m0, s44, 0x800
	global_load_lds_dwordx4 v246, s[42:43]
	ds_read_b128 v[164:167], v197
	ds_read_b128 v[168:171], v197 offset:2048
	s_add_i32 m0, s44, 0xc00
	global_load_lds_dwordx4 v247, s[42:43]
	s_add_i32 m0, s44, 0x1000
	global_load_lds_dwordx4 v248, s[42:43]
	s_add_i32 m0, s44, 0x1400
	global_load_lds_dwordx4 v249, s[42:43]
	s_add_i32 m0, s44, 0x1800
	global_load_lds_dwordx4 v250, s[42:43]
	s_add_i32 m0, s44, 0x1c00
	global_load_lds_dwordx4 v251, s[42:43]
	s_add_u32 s42, s42, 0x80
	s_addc_u32 s43, s43, 0
	s_waitcnt lgkmcnt(0)
	v_mfma_f32_16x16x32_bf16 v[126:129], v[164:167], v[146:149], v[126:129]
	v_mfma_f32_16x16x32_bf16 v[118:121], v[164:167], v[150:153], v[118:121]
	v_mfma_f32_16x16x32_bf16 v[110:113], v[164:167], v[154:157], v[110:113]
	v_mfma_f32_16x16x32_bf16 v[102:105], v[164:167], v[158:161], v[102:105]
	v_mfma_f32_16x16x32_bf16 v[122:125], v[168:171], v[146:149], v[122:125]
	v_mfma_f32_16x16x32_bf16 v[114:117], v[168:171], v[150:153], v[114:117]
	v_mfma_f32_16x16x32_bf16 v[106:109], v[168:171], v[154:157], v[106:109]
	v_mfma_f32_16x16x32_bf16 v[98:101], v[168:171], v[158:161], v[98:101]
	s_waitcnt lgkmcnt(0)
	ds_read_b128 v[216:219], v199 offset:1024
	ds_read_b128 v[220:223], v199 offset:3072
	ds_read_b128 v[224:227], v199 offset:5120
	ds_read_b128 v[240:243], v199 offset:7168
	ds_read_b128 v[164:167], v197 offset:1024
	ds_read_b128 v[168:171], v197 offset:3072
	s_waitcnt lgkmcnt(0)
	v_mfma_f32_16x16x32_bf16 v[126:129], v[164:167], v[216:219], v[126:129]
	v_mfma_f32_16x16x32_bf16 v[118:121], v[164:167], v[220:223], v[118:121]
	v_mfma_f32_16x16x32_bf16 v[110:113], v[164:167], v[224:227], v[110:113]
	v_mfma_f32_16x16x32_bf16 v[102:105], v[164:167], v[240:243], v[102:105]
	v_mfma_f32_16x16x32_bf16 v[122:125], v[168:171], v[216:219], v[122:125]
	v_mfma_f32_16x16x32_bf16 v[114:117], v[168:171], v[220:223], v[114:117]
	v_mfma_f32_16x16x32_bf16 v[106:109], v[168:171], v[224:227], v[106:109]
	v_mfma_f32_16x16x32_bf16 v[98:101], v[168:171], v[240:243], v[98:101]
	s_waitcnt lgkmcnt(0)
	s_waitcnt vmcnt(0)
	s_barrier
	s_add_i32 m0, s45, 0x0
	global_load_lds_dwordx4 v244, s[42:43]
	s_add_i32 m0, s45, 0x400
	global_load_lds_dwordx4 v245, s[42:43]
	s_add_i32 m0, s45, 0x800
	global_load_lds_dwordx4 v246, s[42:43]
	s_add_i32 m0, s45, 0xc00
	global_load_lds_dwordx4 v247, s[42:43]
	s_add_i32 m0, s45, 0x1000
	global_load_lds_dwordx4 v248, s[42:43]
	s_add_i32 m0, s45, 0x1400
	global_load_lds_dwordx4 v249, s[42:43]
	s_add_i32 m0, s45, 0x1800
	global_load_lds_dwordx4 v250, s[42:43]
	s_add_i32 m0, s45, 0x1c00
	global_load_lds_dwordx4 v251, s[42:43]
	s_add_u32 s42, s42, 0x80
	s_addc_u32 s43, s43, 0
	v_readfirstlane_b32 s87, v202
	s_nop 0
	s_cmp_lg_u32 s87, 20
	s_cselect_b32 s87, 1, 0
	s_nop 7
	s_nop 3
	s_branch .LgA_done
.LgA_lite1:
	s_mov_b32 s46, 0
.LgAl1_loop:
	s_waitcnt lgkmcnt(0)
	s_waitcnt lgkmcnt(0)
	s_waitcnt lgkmcnt(0)
	s_waitcnt lgkmcnt(0)
	s_cmp_eq_u32 s47, 0
	s_cbranch_scc1 .LgAl1_w0
	s_mov_b32 s47, 0
	s_waitcnt vmcnt(16)
	s_branch .LgAl1_w1

; DI void g_dma(const bf16_t* __restrict__ base, const unsigned (&off)[8], int ko, unsigned char* stage, int w) {
; #pragma unroll
;   for (int u = 0; u < 8; ++u)
;     __builtin_amdgcn_global_load_lds((const unsigned*)(base + (off[u] + ko)), (lds_u32*)(stage + (w * 8 + u) * 1024), 16, 0, 0);
; }
;     ...
;   for (int kt = 0; kt < KT; kt += 2) {
;     g_dma(base, off, (kt + 1) * kstep, buf1, w);
;     g_compute(buf0, ra, rb, acc);
;     asm volatile("s_waitcnt vmcnt(0)" ::: "memory");
;     __syncthreads();
;     const bool last = kt + 2 >= KT;
;     g_dma(last ? nbase : base, off, last ? 0 : (kt + 2) * kstep, buf0, w);
;     g_compute(buf1, ra, rb, acc);
;     asm volatile("s_waitcnt vmcnt(0)" ::: "memory");
;     __syncthreads();
;   }
.LgAl1_w1:
	s_barrier
	s_add_i32 m0, s44, 0x0
	global_load_lds_dwordx4 v244, s[40:41]
	s_add_i32 m0, s44, 0x400
	global_load_lds_dwordx4 v245, s[40:41]
	s_add_i32 m0, s44, 0x800
	global_load_lds_dwordx4 v246, s[40:41]
	s_add_i32 m0, s44, 0xc00
	global_load_lds_dwordx4 v247, s[40:41]
	s_add_i32 m0, s44, 0x1000
	global_load_lds_dwordx4 v248, s[40:41]
	s_add_i32 m0, s44, 0x1400
	global_load_lds_dwordx4 v249, s[40:41]
	s_add_i32 m0, s44, 0x1800
	global_load_lds_dwordx4 v250, s[40:41]
	s_add_i32 m0, s44, 0x1c00
	global_load_lds_dwordx4 v251, s[40:41]
	s_add_u32 s40, s40, 0x80
	s_addc_u32 s41, s41, 0
	s_waitcnt lgkmcnt(0)
	s_waitcnt lgkmcnt(0)
	s_waitcnt lgkmcnt(0)
	s_waitcnt lgkmcnt(0)
	s_waitcnt vmcnt(0)
	s_barrier
	s_add_i32 m0, s45, 0x0
	global_load_lds_dwordx4 v244, s[40:41]
	s_add_i32 m0, s45, 0x400
	global_load_lds_dwordx4 v245, s[40:41]
	s_add_i32 m0, s45, 0x800
	global_load_lds_dwordx4 v246, s[40:41]
	s_add_i32 m0, s45, 0xc00
	global_load_lds_dwordx4 v247, s[40:41]
	s_add_i32 m0, s45, 0x1000
	global_load_lds_dwordx4 v248, s[40:41]
	s_add_i32 m0, s45, 0x1400
	global_load_lds_dwordx4 v249, s[40:41]
	s_add_i32 m0, s45, 0x1800
	global_load_lds_dwordx4 v250, s[40:41]
	s_add_i32 m0, s45, 0x1c00
	global_load_lds_dwordx4 v251, s[40:41]
	s_add_u32 s40, s40, 0x80
	s_addc_u32 s41, s41, 0
	s_add_i32 s46, s46, 1
	s_cmp_lt_u32 s46, 7
	s_cbranch_scc1 .LgAl1_loop
	s_waitcnt lgkmcnt(0)
	s_waitcnt lgkmcnt(0)
	s_waitcnt lgkmcnt(0)
	s_waitcnt lgkmcnt(0)
	s_waitcnt vmcnt(0)
	s_barrier
	s_add_i32 m0, s44, 0x0
	global_load_lds_dwordx4 v244, s[42:43]
	s_add_i32 m0, s44, 0x400
	global_load_lds_dwordx4 v245, s[42:43]
	s_add_i32 m0, s44, 0x800
	global_load_lds_dwordx4 v246, s[42:43]
	s_add_i32 m0, s44, 0xc00
	global_load_lds_dwordx4 v247, s[42:43]
	s_add_i32 m0, s44, 0x1000
	global_load_lds_dwordx4 v248, s[42:43]
	s_add_i32 m0, s44, 0x1400
	global_load_lds_dwordx4 v249, s[42:43]
	s_add_i32 m0, s44, 0x1800
	global_load_lds_dwordx4 v250, s[42:43]
	s_add_i32 m0, s44, 0x1c00
	global_load_lds_dwordx4 v251, s[42:43]
	s_add_u32 s42, s42, 0x80
	s_addc_u32 s43, s43, 0
	s_waitcnt lgkmcnt(0)
	s_waitcnt lgkmcnt(0)
	s_waitcnt lgkmcnt(0)
	s_waitcnt lgkmcnt(0)
	s_waitcnt vmcnt(0)
	s_barrier
	s_add_i32 m0, s45, 0x0
	global_load_lds_dwordx4 v244, s[42:43]
	s_add_i32 m0, s45, 0x400
	global_load_lds_dwordx4 v245, s[42:43]
	s_add_i32 m0, s45, 0x800
	global_load_lds_dwordx4 v246, s[42:43]
	s_add_i32 m0, s45, 0xc00
	global_load_lds_dwordx4 v247, s[42:43]
	s_add_i32 m0, s45, 0x1000
	global_load_lds_dwordx4 v248, s[42:43]
	s_add_i32 m0, s45, 0x1400
	global_load_lds_dwordx4 v249, s[42:43]
	s_add_i32 m0, s45, 0x1800
	global_load_lds_dwordx4 v250, s[42:43]
	s_add_i32 m0, s45, 0x1c00
	global_load_lds_dwordx4 v251, s[42:43]
	s_add_u32 s42, s42, 0x80
	s_addc_u32 s43, s43, 0
	v_readfirstlane_b32 s87, v202
	s_nop 0
	s_cmp_lg_u32 s87, 20
	s_cselect_b32 s87, 1, 0
	s_nop 7
	s_nop 3
	s_branch .LgA_done

; DI unsigned pk2(float lo, float hi) { f32x2 v = {lo, hi}; bf16x2_t b = __builtin_convertvector(v, bf16x2_t); return __builtin_bit_cast(unsigned, b); }
; DI int my_tid() { int t = threadIdx.x; asm volatile("" : "+v"(t)); return t; }
; DI void phaseA_epilogue(const Params& p, int layer, int mt, int nt, const f32x4 (&acc)[8][4], const float* rs_s) {
;   const int tid = my_tid(), lane = tid & 63, w = tid >> 6, wa = w >> 2, wb = w & 3, qi = lane & 15, quad = lane >> 4;
;   if (nt >= 21) {
;     bf16_t* dstb; int nh, head;
;     if (nt < 23) { dstb = p.sbvt(); nh = 8; head = (nt - 21) * 4 + wb; } else if (wb < 2) { dstb = p.vst(); nh = 2; head = wb; } else { dstb = p.vwt(); nh = 2; head = wb - 2; }
;     const int tok0 = mt * 256, b = tok0 >> 11;
; #pragma unroll
;     for (int ip = 0; ip < 4; ++ip) {
;       const int tl = wa * 128 + ip * 32 + quad * 8;
;       const f32x4 ra = *(const f32x4*)(rs_s + tl), rb2 = *(const f32x4*)(rs_s + tl + 4);
;       const int sq = (tok0 & 2047) + tl;
; #pragma unroll
;       for (int j = 0; j < 4; ++j) {
;         const int d = (j >> 1) * 32 + (qi >> 2) * 8 + (j & 1) * 4 + (qi & 3);
;         const f32x4 v0 = acc[2 * ip][j] * ra, v1 = acc[2 * ip + 1][j] * rb2;
;         bf16_t* dst = dstb + (long)(b * nh + head) * 64 * SEQ + (long)(sq >> 5) * 2048 + d * 32 + (sq & 31);
;         *(u32x4*)dst = (u32x4){pk2(v0[0], v0[1]), pk2(v0[2], v0[3]), pk2(v1[0], v1[1]), pk2(v1[2], v1[3])};
;       }
;     }
;     return;
;   }
;   const bool headtype = nt < 4 || (nt >= 6 && nt < 10);
;   const bool rot = nt == 6 || nt == 7 || nt == 9;
;   f32x4 csr[2][2], snr[2][2];
; #pragma unroll
;   for (int j = 0; j < 4; ++j) {
;     if (rot && (j & 1) == 0) {
; #pragma unroll
;       for (int jj = 0; jj < 2; ++jj) {
;         const long tokj = (long)mt * 256 + wb * 64 + (j >> 1) * 32 + (qi >> 2) * 8 + jj * 4 + (qi & 3);
; #pragma unroll
;         for (int i = 0; i < 2; ++i) { csr[jj][i] = *(const f32x4*)(p.cosT() + tokj * 32 + quad * 8 + i * 4); snr[jj][i] = *(const f32x4*)(p.sinT() + tokj * 32 + quad * 8 + i * 4); }
.Lmy_eA_compiler:
.LgA_done:
	v_mov_b32_e32 v171, v210
	s_nop 0
	v_ashrrev_i32_e32 v169, 8, v171
	v_bfe_u32 v0, v171, 6, 2
	v_and_b32_e32 v131, 15, v171
	v_bfe_u32 v170, v171, 4, 2
	s_and_saveexec_b64 s[10:11], s[8:9]
	s_xor_b64 s[12:13], exec, s[10:11]
	s_cbranch_execz .LBB0_487
	v_cmp_lt_i32_e32 vcc, 8, v202
	s_mov_b64 s[10:11], 0
	v_cmp_eq_u32_e64 s[56:57], 9, v202
	s_and_saveexec_b64 s[8:9], vcc
	s_xor_b64 s[8:9], exec, s[8:9]
	s_and_b64 s[10:11], s[56:57], exec
	s_or_saveexec_b64 s[8:9], s[8:9]
	v_add_u32_e32 v130, -6, v202
	v_cmp_gt_u32_e64 s[58:59], 2, v130
	s_xor_b64 exec, exec, s[8:9]
	s_andn2_b64 s[10:11], s[10:11], exec
	s_and_b64 s[28:29], s[58:59], exec
	s_or_b64 s[10:11], s[10:11], s[28:29]
	s_or_b64 exec, exec, s[8:9]
	v_lshlrev_b32_e32 v130, 1, v131
	v_lshlrev_b32_e32 v0, 6, v0
	v_and_b32_e32 v130, 24, v130
	v_and_b32_e32 v131, 3, v171
	v_lshlrev_b64 v[164:165], 8, v[162:163]
	v_or3_b32 v205, v0, v130, v131
	v_or_b32_e32 v180, v164, v205
	v_mov_b32_e32 v181, v165
	v_lshlrev_b32_e32 v0, 5, v170
	v_lshl_add_u64 v[172:173], s[38:39], 0, v[0:1]
	v_lshl_add_u64 v[174:175], s[60:61], 0, v[0:1]
	v_lshlrev_b64 v[176:177], 7, v[180:181]
	s_and_saveexec_b64 s[8:9], s[10:11]
	s_cbranch_execz .LBB0_282
	v_lshl_add_u64 v[130:131], v[172:173], 0, v[176:177]
	v_lshl_add_u64 v[132:133], v[174:175], 0, v[176:177]
	global_load_dwordx4 v[146:149], v[130:131], off offset:16
	global_load_dwordx4 v[150:153], v[130:131], off
	global_load_dwordx4 v[154:157], v[132:133], off offset:16
	global_load_dwordx4 v[158:161], v[132:133], off
	v_or_b32_e32 v130, 0x200, v176
	v_mov_b32_e32 v131, v177
	v_lshl_add_u64 v[134:135], v[172:173], 0, v[130:131]
	v_lshl_add_u64 v[142:143], v[174:175], 0, v[130:131]
	global_load_dwordx4 v[130:133], v[134:135], off offset:16
	s_nop 0
	global_load_dwordx4 v[134:137], v[134:135], off
	s_nop 0
	global_load_dwordx4 v[138:141], v[142:143], off offset:16
	s_nop 0
	global_load_dwordx4 v[142:145], v[142:143], off
